# MLA K/V LDS-DMA issued from the softmax segment; scan step: LDS reads before DMA issue, probe branches removed
# speedup vs baseline: 1.0036x; 1.0036x over previous
.LBB0_860:
	s_mov_b32 s84, s73
	s_setprio 3
	s_and_b32 s6, s78, 3
	s_mulk_i32 s6, 0x6000
	v_add_u32_e32 v184, s6, v201
	v_add_u32_e32 v70, v184, v199
	ds_read_b128 v[66:69], v70
	ds_read_b128 v[70:73], v70 offset:0x3000
	v_add_u32_e32 v74, v184, v198
	ds_read_b128 v[204:207], v74
	ds_read_b128 v[208:211], v74 offset:0x3000
	v_add_u32_e32 v74, v184, v197
	ds_read_b128 v[212:215], v74
	ds_read_b128 v[216:219], v74 offset:0x3000
	v_add_u32_e32 v74, v184, v196
	ds_read_b128 v[220:223], v74
	ds_read_b128 v[224:227], v74 offset:0x3000
	s_waitcnt lgkmcnt(6)
	v_mfma_f32_32x32x16_bf16 v[82:97], v[66:69], v[142:145], 0
	v_add_u32_e32 v66, v184, v195
	ds_read_b128 v[228:231], v66
	ds_read_b128 v[232:235], v66 offset:0x3000
	s_waitcnt lgkmcnt(6)
	v_mfma_f32_32x32x16_bf16 v[66:81], v[70:73], v[142:145], 0
	v_mfma_f32_32x32x16_bf16 v[82:97], v[204:207], v[138:141], v[82:97]
	v_add_u32_e32 v200, v184, v193
	ds_read_b128 v[204:207], v200
	ds_read_b128 v[236:239], v200 offset:0x3000
	s_waitcnt lgkmcnt(6)
	v_mfma_f32_32x32x16_bf16 v[66:81], v[208:211], v[138:141], v[66:81]
	v_mfma_f32_32x32x16_bf16 v[82:97], v[212:215], v[134:137], v[82:97]
	v_add_u32_e32 v200, v184, v191
	ds_read_b128 v[208:211], v200
	ds_read_b128 v[212:215], v200 offset:0x3000
	s_waitcnt lgkmcnt(6)
	v_mfma_f32_32x32x16_bf16 v[66:81], v[216:219], v[134:137], v[66:81]
	v_mfma_f32_32x32x16_bf16 v[82:97], v[220:223], v[130:133], v[82:97]
	v_add_u32_e32 v200, v184, v190
	ds_read_b128 v[216:219], v200
	ds_read_b128 v[220:223], v200 offset:0x3000
	s_waitcnt lgkmcnt(6)
	v_mfma_f32_32x32x16_bf16 v[66:81], v[224:227], v[130:133], v[66:81]
	v_mfma_f32_32x32x16_bf16 v[82:97], v[228:231], v[126:129], v[82:97]
	v_add_u32_e32 v200, v184, v189
	ds_read_b128 v[224:227], v200
	ds_read_b128 v[228:231], v200 offset:0x3000
	s_waitcnt lgkmcnt(6)
	v_mfma_f32_32x32x16_bf16 v[66:81], v[232:235], v[126:129], v[66:81]
	v_mfma_f32_32x32x16_bf16 v[82:97], v[204:207], v[122:125], v[82:97]
	v_add_u32_e32 v200, v184, v188
	ds_read_b128 v[204:207], v200
	ds_read_b128 v[232:235], v200 offset:0x3000
	s_waitcnt lgkmcnt(6)
	v_mfma_f32_32x32x16_bf16 v[66:81], v[236:239], v[122:125], v[66:81]
	v_mfma_f32_32x32x16_bf16 v[82:97], v[208:211], v[118:121], v[82:97]
	v_add_u32_e32 v200, v184, v187
	ds_read_b128 v[208:211], v200
	ds_read_b128 v[236:239], v200 offset:0x3000
	s_waitcnt lgkmcnt(6)
	v_mfma_f32_32x32x16_bf16 v[66:81], v[212:215], v[118:121], v[66:81]
	v_mfma_f32_32x32x16_bf16 v[82:97], v[216:219], v[114:117], v[82:97]
	v_add_u32_e32 v184, v184, v186
	ds_read_b128 v[212:215], v184
	ds_read_b128 v[216:219], v184 offset:0x3000
	s_waitcnt lgkmcnt(6)
	v_mfma_f32_32x32x16_bf16 v[66:81], v[220:223], v[114:117], v[66:81]
	v_mfma_f32_32x32x16_bf16 v[82:97], v[224:227], v[110:113], v[82:97]
	s_waitcnt lgkmcnt(4)
	v_mfma_f32_32x32x16_bf16 v[66:81], v[228:231], v[110:113], v[66:81]
	v_mfma_f32_32x32x16_bf16 v[82:97], v[204:207], v[106:109], v[82:97]
	s_waitcnt lgkmcnt(2)
	v_mfma_f32_32x32x16_bf16 v[66:81], v[232:235], v[106:109], v[66:81]
	v_mfma_f32_32x32x16_bf16 v[82:97], v[208:211], v[102:105], v[82:97]
	s_waitcnt lgkmcnt(0)
	v_mfma_f32_32x32x16_bf16 v[66:81], v[236:239], v[102:105], v[66:81]
	s_lshl_b32 s85, s84, 14
	v_add_u32_e32 v184, s85, v185
	ds_read_b64_tr_b16 v[204:205], v184 offset:0
	ds_read_b64_tr_b16 v[206:207], v184 offset:0x800
	ds_read_b64_tr_b16 v[208:209], v184 offset:0x1000
	v_mfma_f32_32x32x16_bf16 v[82:97], v[212:215], v[98:101], v[82:97]
	ds_read_b64_tr_b16 v[210:211], v184 offset:0x1800
	ds_read_b64_tr_b16 v[212:213], v184 offset:0x2000
	ds_read_b64_tr_b16 v[214:215], v184 offset:0x2800
	ds_read_b64_tr_b16 v[220:221], v184 offset:0x3000
	ds_read_b64_tr_b16 v[222:223], v184 offset:0x3800
	s_waitcnt lgkmcnt(0)
	v_mfma_f32_32x32x16_bf16 v[66:81], v[216:219], v[98:101], v[66:81]
	v_mfma_f32_32x32x16_bf16 v[2:17], v[146:149], v[204:207], v[2:17]
	ds_read_b64_tr_b16 v[204:205], v184 offset:0x200
	ds_read_b64_tr_b16 v[206:207], v184 offset:0xa00
	v_mfma_f32_32x32x16_bf16 v[2:17], v[150:153], v[208:211], v[2:17]
	ds_read_b64_tr_b16 v[208:209], v184 offset:0x1200
	ds_read_b64_tr_b16 v[210:211], v184 offset:0x1a00
	v_mfma_f32_32x32x16_bf16 v[2:17], v[158:161], v[212:215], v[2:17]
	ds_read_b64_tr_b16 v[212:213], v184 offset:0x2200
	ds_read_b64_tr_b16 v[214:215], v184 offset:0x2a00
	ds_read_b64_tr_b16 v[216:217], v184 offset:0x3200
	ds_read_b64_tr_b16 v[218:219], v184 offset:0x3a00
	s_waitcnt lgkmcnt(0)
	v_mfma_f32_32x32x16_bf16 v[2:17], v[154:157], v[220:223], v[2:17]
	v_mfma_f32_32x32x16_bf16 v[50:65], v[146:149], v[204:207], v[50:65]
	ds_read_b64_tr_b16 v[204:205], v184 offset:0x400
	ds_read_b64_tr_b16 v[206:207], v184 offset:0xc00
	v_mfma_f32_32x32x16_bf16 v[50:65], v[150:153], v[208:211], v[50:65]
	ds_read_b64_tr_b16 v[208:209], v184 offset:0x1400
	ds_read_b64_tr_b16 v[210:211], v184 offset:0x1c00
	v_mfma_f32_32x32x16_bf16 v[50:65], v[158:161], v[212:215], v[50:65]
	ds_read_b64_tr_b16 v[212:213], v184 offset:0x2400
	ds_read_b64_tr_b16 v[214:215], v184 offset:0x2c00
	ds_read_b64_tr_b16 v[220:221], v184 offset:0x3400
	ds_read_b64_tr_b16 v[222:223], v184 offset:0x3c00
	s_waitcnt lgkmcnt(0)
	v_mfma_f32_32x32x16_bf16 v[50:65], v[154:157], v[216:219], v[50:65]
	v_mfma_f32_32x32x16_bf16 v[34:49], v[146:149], v[204:207], v[34:49]
	ds_read_b64_tr_b16 v[204:205], v184 offset:0x600
	ds_read_b64_tr_b16 v[206:207], v184 offset:0xe00
	v_mfma_f32_32x32x16_bf16 v[34:49], v[150:153], v[208:211], v[34:49]
	ds_read_b64_tr_b16 v[208:209], v184 offset:0x1600
	ds_read_b64_tr_b16 v[210:211], v184 offset:0x1e00
	v_mfma_f32_32x32x16_bf16 v[34:49], v[158:161], v[212:215], v[34:49]
	ds_read_b64_tr_b16 v[212:213], v184 offset:0x2600
	ds_read_b64_tr_b16 v[214:215], v184 offset:0x2e00
	ds_read_b64_tr_b16 v[216:217], v184 offset:0x3600
	ds_read_b64_tr_b16 v[218:219], v184 offset:0x3e00
	s_waitcnt lgkmcnt(0)
	v_mfma_f32_32x32x16_bf16 v[34:49], v[154:157], v[220:223], v[34:49]
	v_mfma_f32_32x32x16_bf16 v[18:33], v[146:149], v[204:207], v[18:33]
	s_nop 0
	s_waitcnt lgkmcnt(0)
	s_barrier
	v_mfma_f32_32x32x16_bf16 v[18:33], v[150:153], v[208:211], v[18:33]
	v_mfma_f32_32x32x16_bf16 v[18:33], v[158:161], v[212:215], v[18:33]
	v_mfma_f32_32x32x16_bf16 v[18:33], v[154:157], v[216:219], v[18:33]
	s_setprio 0
	s_add_i32 s6, s78, 2
	s_and_b32 s6, s6, 3
	s_mulk_i32 s6, 0x6000
	s_add_i32 s6, s6, s80
	s_mov_b32 m0, s6
	s_lshl_b32 s75, s79, 14
	global_load_lds_dwordx4 v[178:179], off
	s_add_i32 m0, s6, 0x2000
	s_add_i32 s73, s75, s76
	global_load_lds_dwordx4 v[176:177], off
	s_add_i32 m0, s6, 0x4000
	v_lshl_add_u64 v[240:241], v[180:181], 0, s[28:29]
	global_load_lds_dwordx4 v[174:175], off
	v_lshl_add_u64 v[242:243], v[240:241], 0, s[12:13]
	s_mov_b32 m0, s73
	s_add_i32 s74, s73, 0x2000
	global_load_lds_dwordx4 v[242:243], off
	v_lshl_add_u64 v[240:241], v[240:241], 0, s[14:15]
	s_mov_b32 m0, s74
	s_nop 0
	global_load_lds_dwordx4 v[240:241], off
	v_max_f32_e32 v146, v83, v83
	v_max_f32_e32 v147, v82, v82
	v_max_f32_e32 v146, v147, v146
	v_max3_f32 v146, v146, v84, v85
	v_max3_f32 v146, v146, v86, v87
	v_max3_f32 v146, v146, v88, v89
	v_max3_f32 v146, v146, v90, v91
	v_max3_f32 v146, v146, v92, v93
	v_max3_f32 v146, v146, v94, v95
	v_max3_f32 v146, v146, v96, v97
	v_max3_f32 v146, v146, v66, v67
	v_max3_f32 v146, v146, v68, v69
	v_max3_f32 v146, v146, v70, v71
	v_max3_f32 v146, v146, v72, v73
	v_max3_f32 v146, v146, v74, v75
	v_max3_f32 v146, v146, v76, v77
	v_max3_f32 v146, v146, v78, v79
	v_max3_f32 v146, v146, v80, v81
	v_mov_b32_e32 v147, v146
	s_nop 1
	v_permlane32_swap_b32_e32 v146, v147
	v_max_f32_e32 v147, v147, v147
	v_max_f32_e32 v146, v146, v146
	v_max_f32_e32 v146, v146, v147
	v_sub_f32_e32 v147, v146, v194
	v_cmp_ge_f32_e32 vcc, s56, v147
	v_max_f32_e32 v147, v194, v194
	v_max_f32_e32 v147, v147, v146
	v_sub_f32_e32 v146, v194, v147
	v_mul_f32_e32 v146, 0x3dd53b94, v146
	v_exp_f32_e32 v146, v146
	s_cmp_eq_u64 vcc, exec
	s_cselect_b64 s[6:7], -1, 0
	v_cndmask_b32_e64 v146, v146, 1.0, s[6:7]
	v_cmp_gt_f32_e32 vcc, 1.0, v146
	s_cbranch_vccz .LBB0_864
	s_and_saveexec_b64 s[30:31], s[4:5]
	ds_write_b32 v183, v146 offset:128
	s_or_b64 exec, exec, s[30:31]
	s_waitcnt lgkmcnt(0)
	v_add_u32_e32 v160, s72, v166
	ds_read_b128 v[148:151], v160 offset:224
	ds_read_b128 v[152:155], v160 offset:192
	ds_read_b128 v[156:159], v160 offset:160
	ds_read_b128 v[204:207], v160 offset:128
	s_waitcnt lgkmcnt(3)
	v_pk_mul_f32 v[14:15], v[14:15], v[148:149]
	s_waitcnt lgkmcnt(2)
	v_pk_mul_f32 v[10:11], v[10:11], v[152:153]
	s_waitcnt lgkmcnt(1)
	v_pk_mul_f32 v[6:7], v[6:7], v[156:157]
	v_pk_mul_f32 v[16:17], v[16:17], v[150:151]
	v_pk_mul_f32 v[12:13], v[12:13], v[154:155]
	v_pk_mul_f32 v[8:9], v[8:9], v[158:159]
	s_waitcnt lgkmcnt(0)
	v_pk_mul_f32 v[4:5], v[4:5], v[206:207]
	v_pk_mul_f32 v[2:3], v[2:3], v[204:205]
	v_pk_mul_f32 v[62:63], v[62:63], v[148:149]
	v_pk_mul_f32 v[58:59], v[58:59], v[152:153]
	v_pk_mul_f32 v[54:55], v[54:55], v[156:157]
	v_pk_mul_f32 v[64:65], v[64:65], v[150:151]
	v_pk_mul_f32 v[60:61], v[60:61], v[154:155]
	v_pk_mul_f32 v[56:57], v[56:57], v[158:159]
	v_pk_mul_f32 v[52:53], v[52:53], v[206:207]
	v_pk_mul_f32 v[50:51], v[50:51], v[204:205]
	v_pk_mul_f32 v[46:47], v[46:47], v[148:149]
	v_pk_mul_f32 v[42:43], v[42:43], v[152:153]
	v_pk_mul_f32 v[38:39], v[38:39], v[156:157]
	v_pk_mul_f32 v[48:49], v[48:49], v[150:151]
	v_pk_mul_f32 v[44:45], v[44:45], v[154:155]
	v_pk_mul_f32 v[40:41], v[40:41], v[158:159]
	v_pk_mul_f32 v[36:37], v[36:37], v[206:207]
	v_pk_mul_f32 v[34:35], v[34:35], v[204:205]
	v_pk_mul_f32 v[30:31], v[30:31], v[148:149]
	v_pk_mul_f32 v[26:27], v[26:27], v[152:153]
	v_pk_mul_f32 v[22:23], v[22:23], v[156:157]
	v_pk_mul_f32 v[32:33], v[32:33], v[150:151]
	v_pk_mul_f32 v[28:29], v[28:29], v[154:155]
	v_pk_mul_f32 v[24:25], v[24:25], v[158:159]
	v_pk_mul_f32 v[20:21], v[20:21], v[206:207]
	v_pk_mul_f32 v[18:19], v[18:19], v[204:205]
.LBB0_864:
	v_cndmask_b32_e64 v194, v147, v194, s[6:7]
	v_mul_f32_e32 v147, 0xbdd53b94, v194
	v_fmamk_f32 v82, v82, 0x3dd53b94, v147
	v_fmamk_f32 v83, v83, 0x3dd53b94, v147
	v_fmamk_f32 v84, v84, 0x3dd53b94, v147
	v_fmamk_f32 v85, v85, 0x3dd53b94, v147
	v_fmamk_f32 v86, v86, 0x3dd53b94, v147
	v_fmamk_f32 v87, v87, 0x3dd53b94, v147
	v_fmamk_f32 v88, v88, 0x3dd53b94, v147
	v_fmamk_f32 v89, v89, 0x3dd53b94, v147
	v_fmamk_f32 v90, v90, 0x3dd53b94, v147
	v_fmamk_f32 v91, v91, 0x3dd53b94, v147
	v_fmamk_f32 v92, v92, 0x3dd53b94, v147
	v_fmamk_f32 v93, v93, 0x3dd53b94, v147
	v_fmamk_f32 v94, v94, 0x3dd53b94, v147
	v_fmamk_f32 v95, v95, 0x3dd53b94, v147
	v_fmamk_f32 v96, v96, 0x3dd53b94, v147
	v_fmamk_f32 v97, v97, 0x3dd53b94, v147
	v_fmamk_f32 v66, v66, 0x3dd53b94, v147
	v_fmamk_f32 v67, v67, 0x3dd53b94, v147
	v_fmamk_f32 v68, v68, 0x3dd53b94, v147
	v_fmamk_f32 v69, v69, 0x3dd53b94, v147
	v_fmamk_f32 v70, v70, 0x3dd53b94, v147
	v_fmamk_f32 v71, v71, 0x3dd53b94, v147
	v_fmamk_f32 v72, v72, 0x3dd53b94, v147
	v_fmamk_f32 v73, v73, 0x3dd53b94, v147
	v_fmamk_f32 v74, v74, 0x3dd53b94, v147
	v_fmamk_f32 v75, v75, 0x3dd53b94, v147
	v_fmamk_f32 v76, v76, 0x3dd53b94, v147
	v_fmamk_f32 v77, v77, 0x3dd53b94, v147
	v_fmamk_f32 v78, v78, 0x3dd53b94, v147
	v_fmamk_f32 v79, v79, 0x3dd53b94, v147
	v_fmamk_f32 v80, v80, 0x3dd53b94, v147
	v_fmac_f32_e32 v147, 0x3dd53b94, v81
	v_exp_f32_e32 v81, v82
	v_exp_f32_e32 v82, v83
	v_exp_f32_e32 v83, v84
	v_exp_f32_e32 v84, v85
	v_exp_f32_e32 v85, v86
	v_exp_f32_e32 v86, v87
	v_exp_f32_e32 v87, v88
	v_exp_f32_e32 v88, v89
	v_exp_f32_e32 v89, v90
	v_exp_f32_e32 v90, v91
	v_exp_f32_e32 v91, v92
	v_exp_f32_e32 v92, v93
	v_exp_f32_e32 v93, v94
	v_exp_f32_e32 v94, v95
	v_exp_f32_e32 v95, v96
	v_exp_f32_e32 v96, v97
	v_exp_f32_e32 v97, v147
	v_add_f32_e32 v147, 0, v81
	v_add_f32_e32 v147, v82, v147
	v_add_f32_e32 v147, v83, v147
	v_add_f32_e32 v147, v84, v147
	v_add_f32_e32 v147, v85, v147
	v_add_f32_e32 v147, v86, v147
	v_add_f32_e32 v147, v87, v147
	v_add_f32_e32 v147, v88, v147
	v_add_f32_e32 v147, v89, v147
	v_add_f32_e32 v147, v90, v147
	v_add_f32_e32 v147, v91, v147
	v_add_f32_e32 v147, v92, v147
	v_exp_f32_e32 v66, v66
	v_add_f32_e32 v147, v93, v147
	v_exp_f32_e32 v67, v67
	v_add_f32_e32 v147, v94, v147
	v_exp_f32_e32 v68, v68
	v_add_f32_e32 v147, v95, v147
	v_exp_f32_e32 v69, v69
	v_add_f32_e32 v147, v96, v147
	v_exp_f32_e32 v70, v70
	v_add_f32_e32 v147, v66, v147
	v_exp_f32_e32 v71, v71
	v_add_f32_e32 v147, v67, v147
	v_exp_f32_e32 v72, v72
	v_add_f32_e32 v147, v68, v147
	v_exp_f32_e32 v73, v73
	v_add_f32_e32 v147, v69, v147
	v_exp_f32_e32 v74, v74
	v_add_f32_e32 v147, v70, v147
	v_exp_f32_e32 v75, v75
	v_add_f32_e32 v147, v71, v147
	v_exp_f32_e32 v76, v76
	v_add_f32_e32 v147, v72, v147
	v_exp_f32_e32 v77, v77
	v_add_f32_e32 v147, v73, v147
	v_exp_f32_e32 v78, v78
	v_add_f32_e32 v147, v74, v147
	v_exp_f32_e32 v79, v79
	v_add_f32_e32 v147, v75, v147
	v_exp_f32_e32 v80, v80
	v_add_f32_e32 v147, v76, v147
	v_add_f32_e32 v147, v77, v147
	v_add_f32_e32 v147, v78, v147
	v_add_f32_e32 v147, v79, v147
	v_add_f32_e32 v147, v80, v147
	v_add_f32_e32 v147, v97, v147
	v_mov_b32_e32 v148, v147
	s_nop 1
	v_permlane32_swap_b32_e32 v147, v148
	v_add_f32_e32 v200, v147, v148
	s_add_u32 s28, s28, 0x80000
	v_fmac_f32_e32 v200, v202, v146
	v_cvt_pk_bf16_f32 v146, v81, v82
	v_cvt_pk_bf16_f32 v147, v83, v84
	v_cvt_pk_bf16_f32 v148, v85, v86
	v_cvt_pk_bf16_f32 v149, v87, v88
	v_cvt_pk_bf16_f32 v150, v89, v90
	v_cvt_pk_bf16_f32 v151, v91, v92
	v_cvt_pk_bf16_f32 v152, v93, v94
	v_cvt_pk_bf16_f32 v153, v95, v96
	v_cvt_pk_bf16_f32 v158, v66, v67
	v_cvt_pk_bf16_f32 v159, v68, v69
	v_cvt_pk_bf16_f32 v160, v70, v71
	v_cvt_pk_bf16_f32 v161, v72, v73
	v_cvt_pk_bf16_f32 v154, v74, v75
	v_cvt_pk_bf16_f32 v155, v76, v77
	v_cvt_pk_bf16_f32 v156, v78, v79
	v_cvt_pk_bf16_f32 v157, v80, v97
	s_addc_u32 s29, s29, 0
	s_add_i32 s78, s78, 1
	v_permlane32_swap_b32_e32 v146, v148
	v_permlane32_swap_b32_e32 v147, v149
	v_permlane32_swap_b32_e32 v150, v152
	v_permlane32_swap_b32_e32 v151, v153
	v_permlane32_swap_b32_e32 v158, v160
	v_permlane32_swap_b32_e32 v159, v161
	v_permlane32_swap_b32_e32 v154, v156
	v_permlane32_swap_b32_e32 v155, v157
	v_lshl_add_u64 v[174:175], v[174:175], 0, v[172:173]
	v_lshl_add_u64 v[176:177], v[176:177], 0, v[170:171]
	s_cmp_eq_u32 s83, s28
	v_lshl_add_u64 v[178:179], v[178:179], 0, v[168:169]
	s_waitcnt vmcnt(0)
	s_barrier
	s_cbranch_scc1 .LBB0_866
	s_mov_b32 s73, s77
	s_mov_b32 s77, s79
	s_mov_b32 s79, s84
	v_mov_b32_e32 v202, v200
	s_branch .LBB0_860

.LBB0_1527:
	s_or_b64 exec, exec, s[28:29]
	v_cvt_pk_bf16_f32 v170, v10, v11
	v_cvt_pk_bf16_f32 v171, v12, v13
	v_cvt_pk_bf16_f32 v172, v14, v15
	v_cvt_pk_bf16_f32 v173, v16, v17
	s_and_b64 vcc, exec, s[12:13]
	s_waitcnt lgkmcnt(0)
	v_mfma_f32_16x16x32_bf16 v[134:137], v[170:173], v[134:137], 0
	v_mfma_f32_16x16x32_bf16 v[138:141], v[170:173], v[138:141], 0
	v_cvt_pk_bf16_f32 v170, v18, v19
	v_cvt_pk_bf16_f32 v171, v20, v21
	v_cvt_pk_bf16_f32 v172, v22, v23
	v_cvt_pk_bf16_f32 v173, v24, v25
	s_nop 0
	v_mfma_f32_16x16x32_bf16 v[126:129], v[170:173], v[126:129], v[134:137]
	v_cvt_pk_bf16_f32 v134, v26, v27
	v_cvt_pk_bf16_f32 v135, v28, v29
	v_cvt_pk_bf16_f32 v136, v30, v31
	v_mfma_f32_16x16x32_bf16 v[130:133], v[170:173], v[130:133], v[138:141]
	v_cvt_pk_bf16_f32 v137, v32, v33
	s_nop 3
	v_mfma_f32_16x16x32_bf16 v[118:121], v[134:137], v[118:121], v[126:129]
	v_cvt_pk_bf16_f32 v126, v34, v35
	v_cvt_pk_bf16_f32 v127, v36, v37
	v_cvt_pk_bf16_f32 v128, v38, v39
	v_mfma_f32_16x16x32_bf16 v[122:125], v[134:137], v[122:125], v[130:133]
	v_cvt_pk_bf16_f32 v129, v40, v41
	s_nop 0
	v_mfma_f32_16x16x32_bf16 v[114:117], v[126:129], v[114:117], v[118:121]
	v_mfma_f32_16x16x32_bf16 v[110:113], v[126:129], v[110:113], v[122:125]
	s_cbranch_vccnz .LBB0_1533
	v_mfma_f32_16x16x32_bf16 v[114:117], v[42:45], v[2:5], v[114:117]
	v_mfma_f32_16x16x32_bf16 v[110:113], v[42:45], v[6:9], v[110:113]
.LBB0_1533:
	s_add_i32 s28, s36, 4
	s_cmp_lt_u32 s35, 8
	s_cselect_b32 s26, 0x100, -8
	s_add_i32 s29, s26, s35
	s_and_b64 s[26:27], s[18:19], exec
	s_cselect_b32 s26, s29, s28
	s_lshl_b32 s26, s26, 5
	s_ashr_i32 s27, s26, 31
	v_lshl_add_u64 v[118:119], v[152:153], 0, s[26:27]
	v_mad_u64_u32 v[120:121], s[26:27], v118, s37, v[154:155]
	v_mov_b32_e32 v118, v121
	v_mad_u64_u32 v[118:119], s[26:27], v119, s37, v[118:119]
	v_mov_b32_e32 v121, v118
	v_cvt_pk_bf16_f32 v114, v114, v115
	v_cvt_pk_bf16_f32 v115, v116, v117
	global_store_dwordx2 v[120:121], v[114:115], off
	v_cvt_pk_bf16_f32 v110, v110, v111
	v_cvt_pk_bf16_f32 v111, v112, v113
	v_add_co_u32_e32 v112, vcc, 0x18000, v120
	s_nop 1
	v_addc_co_u32_e32 v113, vcc, 0, v118, vcc
	global_store_dwordx2 v[112:113], v[110:111], off
	v_pk_mul_f32 v[12:13], v[12:13], v[108:109]
	v_pk_mul_f32 v[10:11], v[10:11], v[106:107]
	v_pk_mul_f32 v[16:17], v[16:17], v[100:101]
	v_pk_mul_f32 v[14:15], v[14:15], v[98:99]
	v_pk_mul_f32 v[20:21], v[20:21], v[96:97]
	v_pk_mul_f32 v[18:19], v[18:19], v[94:95]
	v_pk_mul_f32 v[24:25], v[24:25], v[84:85]
	v_pk_mul_f32 v[22:23], v[22:23], v[82:83]
	v_pk_mul_f32 v[28:29], v[28:29], v[80:81]
	v_pk_mul_f32 v[26:27], v[26:27], v[78:79]
	v_pk_mul_f32 v[32:33], v[32:33], v[68:69]
	v_pk_mul_f32 v[30:31], v[30:31], v[66:67]
	v_pk_mul_f32 v[36:37], v[36:37], v[64:65]
	v_pk_mul_f32 v[34:35], v[34:35], v[62:63]
	v_pk_mul_f32 v[40:41], v[40:41], v[52:53]
	v_pk_mul_f32 v[38:39], v[38:39], v[50:51]
	v_mfma_f32_16x16x32_bf16 v[10:13], v[102:105], v[42:45], v[10:13]
	v_mfma_f32_16x16x32_bf16 v[14:17], v[90:93], v[42:45], v[14:17]
	v_mfma_f32_16x16x32_bf16 v[18:21], v[86:89], v[42:45], v[18:21]
	v_mfma_f32_16x16x32_bf16 v[22:25], v[74:77], v[42:45], v[22:25]
	v_mfma_f32_16x16x32_bf16 v[26:29], v[70:73], v[42:45], v[26:29]
	v_mfma_f32_16x16x32_bf16 v[30:33], v[58:61], v[42:45], v[30:33]
	v_mfma_f32_16x16x32_bf16 v[34:37], v[54:57], v[42:45], v[34:37]
	v_mfma_f32_16x16x32_bf16 v[38:41], v[46:49], v[42:45], v[38:41]
	s_add_i32 s35, s35, 1
	s_add_i32 s36, s36, -1
	s_cmp_lg_u32 s36, -5
	s_cbranch_scc1 .LBB0_1504
